# normM/norm2: all gain/scale/shift loads of a row issued together (was 4 serialized round trips per row)
# speedup vs baseline: 1.0065x; 1.0018x over previous
.LBB0_979:
	s_or_b64 exec, exec, s[44:45]
	s_waitcnt vmcnt(0) lgkmcnt(0)
	v_mul_f32_e32 v52, v29, v29
	v_mul_f32_e32 v53, v25, v25
	v_fmac_f32_e32 v52, v28, v28
	v_fmac_f32_e32 v53, v24, v24
	v_fmac_f32_e32 v52, v30, v30
	v_fmac_f32_e32 v53, v26, v26
	v_fmac_f32_e32 v52, v31, v31
	v_fmac_f32_e32 v53, v27, v27
	v_add_f32_e32 v52, v53, v52
	v_mul_f32_e32 v53, v17, v17
	v_fmac_f32_e32 v53, v16, v16
	v_fmac_f32_e32 v53, v18, v18
	v_fmac_f32_e32 v53, v19, v19
	v_add_f32_e32 v52, v53, v52
	v_mul_f32_e32 v53, v21, v21
	v_fmac_f32_e32 v53, v20, v20
	v_fmac_f32_e32 v53, v22, v22
	v_fmac_f32_e32 v53, v23, v23
	v_add_f32_e32 v52, v53, v52
	v_mul_f32_e32 v53, v13, v13
	v_mul_f32_e32 v54, v9, v9
	v_fmac_f32_e32 v53, v12, v12
	v_fmac_f32_e32 v54, v8, v8
	v_fmac_f32_e32 v53, v14, v14
	v_fmac_f32_e32 v54, v10, v10
	v_fmac_f32_e32 v53, v15, v15
	v_fmac_f32_e32 v54, v11, v11
	v_add_f32_e32 v53, v54, v53
	v_mul_f32_e32 v54, v1, v1
	v_fmac_f32_e32 v54, v0, v0
	v_fmac_f32_e32 v54, v2, v2
	v_fmac_f32_e32 v54, v3, v3
	v_add_f32_e32 v53, v54, v53
	v_mul_f32_e32 v54, v5, v5
	v_fmac_f32_e32 v54, v4, v4
	v_fmac_f32_e32 v54, v6, v6
	v_fmac_f32_e32 v54, v7, v7
	v_add_f32_e32 v53, v54, v53
	ds_bpermute_b32 v54, v35, v52
	s_mov_b32 s30, 0x800000
	s_mov_b64 s[42:43], 0x4000
	global_load_dwordx4 v[68:71], v[38:39], off offset:16
	global_load_dwordx4 v[72:75], v[38:39], off
	s_waitcnt lgkmcnt(0)
	v_add_f32_e32 v52, v52, v54
	ds_bpermute_b32 v54, v35, v53
	s_waitcnt lgkmcnt(0)
	v_add_f32_e32 v53, v53, v54
	ds_bpermute_b32 v54, v62, v52
	s_waitcnt lgkmcnt(0)
	v_add_f32_e32 v52, v52, v54
	ds_bpermute_b32 v54, v62, v53
	s_waitcnt lgkmcnt(0)
	v_add_f32_e32 v53, v53, v54
	ds_bpermute_b32 v54, v63, v52
	s_waitcnt lgkmcnt(0)
	v_add_f32_e32 v52, v52, v54
	ds_bpermute_b32 v54, v63, v53
	s_waitcnt lgkmcnt(0)
	v_add_f32_e32 v53, v53, v54
	ds_bpermute_b32 v54, v64, v52
	s_waitcnt lgkmcnt(0)
	v_add_f32_e32 v52, v52, v54
	ds_bpermute_b32 v54, v64, v53
	s_waitcnt lgkmcnt(0)
	v_add_f32_e32 v53, v53, v54
	ds_bpermute_b32 v54, v65, v52
	s_waitcnt lgkmcnt(0)
	v_add_f32_e32 v52, v52, v54
	ds_bpermute_b32 v54, v65, v53
	s_waitcnt lgkmcnt(0)
	v_add_f32_e32 v53, v53, v54
	ds_bpermute_b32 v54, v66, v52
	ds_bpermute_b32 v58, v66, v53
	s_waitcnt lgkmcnt(1)
	v_add_f32_e32 v52, v52, v54
	v_fmamk_f32 v52, v52, 0x3a800000, v191
	v_cmp_gt_f32_e32 vcc, s30, v52
	v_mul_f32_e32 v56, 0x4b800000, v52
	v_min_i32_e32 v54, 0x8000, v32
	v_cndmask_b32_e32 v52, v52, v56, vcc
	v_ashrrev_i32_e32 v54, 12, v54
	v_rsq_f32_e32 v52, v52
	v_mul_i32_i24_e32 v54, 9, v54
	v_ashrrev_i32_e32 v55, 31, v54
	v_lshlrev_b64 v[54:55], 12, v[54:55]
	v_mul_f32_e32 v56, 0x45800000, v52
	v_lshl_add_u64 v[60:61], v[42:43], 0, v[54:55]
	s_movk_i32 s30, 0x4000
	v_cndmask_b32_e32 v52, v52, v56, vcc
	v_add_co_u32_e32 v76, vcc, s30, v60
	v_lshl_add_u64 v[56:57], v[60:61], 0, s[42:43]
	s_mov_b64 s[42:43], 0x3000
	v_addc_co_u32_e32 v77, vcc, 0, v61, vcc
	s_movk_i32 s30, 0x3000
	v_lshl_add_u64 v[54:55], v[60:61], 0, s[42:43]
	v_add_co_u32_e32 v60, vcc, s30, v60
	flat_load_dwordx4 v[76:79], v[76:77]
	s_nop 0
	v_addc_co_u32_e32 v61, vcc, 0, v61, vcc
	flat_load_dwordx4 v[80:83], v[60:61]
	global_load_dwordx4 v[112:115], v[56:57], off offset:16
	global_load_dwordx4 v[116:119], v[54:55], off offset:16
	global_load_dwordx4 v[120:123], v[40:41], off offset:16
	global_load_dwordx4 v[124:127], v[40:41], off
	global_load_dwordx4 v[128:131], v[56:57], off offset:2048
	global_load_dwordx4 v[132:135], v[54:55], off offset:2048
	global_load_dwordx4 v[136:139], v[56:57], off offset:2064
	global_load_dwordx4 v[140:143], v[54:55], off offset:2064
	v_pk_mul_f32 v[30:31], v[30:31], v[52:53] op_sel_hi:[1,0]
	v_pk_mul_f32 v[28:29], v[28:29], v[52:53] op_sel_hi:[1,0]
	s_waitcnt vmcnt(0)
	v_pk_mul_f32 v[30:31], v[74:75], v[30:31]
	v_pk_mul_f32 v[28:29], v[72:73], v[28:29]
	v_pk_mul_f32 v[26:27], v[26:27], v[52:53] op_sel_hi:[1,0]
	v_pk_mul_f32 v[24:25], v[24:25], v[52:53] op_sel_hi:[1,0]
	v_pk_mul_f32 v[26:27], v[70:71], v[26:27]
	v_pk_mul_f32 v[24:25], v[68:69], v[24:25]
	s_mov_b32 s30, 0xc944000
	v_pk_mul_f32 v[18:19], v[18:19], v[52:53] op_sel_hi:[1,0]
	v_pk_mul_f32 v[16:17], v[16:17], v[52:53] op_sel_hi:[1,0]
	v_pk_mul_f32 v[22:23], v[22:23], v[52:53] op_sel_hi:[1,0]
	v_pk_mul_f32 v[20:21], v[20:21], v[52:53] op_sel_hi:[1,0]
	s_waitcnt lgkmcnt(0)
	v_pk_add_f32 v[60:61], v[78:79], 1.0 op_sel_hi:[1,0]
	v_pk_add_f32 v[72:73], v[76:77], 1.0 op_sel_hi:[1,0]
	v_pk_fma_f32 v[60:61], v[60:61], v[30:31], v[82:83]
	v_pk_fma_f32 v[76:77], v[72:73], v[28:29], v[80:81]
	s_nop 1
	v_mov_b64_e32 v[28:29], v[112:113]
	v_mov_b64_e32 v[30:31], v[114:115]
	s_nop 1
	v_mov_b64_e32 v[72:73], v[116:117]
	v_mov_b64_e32 v[74:75], v[118:119]
	s_waitcnt vmcnt(0) lgkmcnt(0)
	v_pk_add_f32 v[30:31], v[30:31], 1.0 op_sel_hi:[1,0]
	v_pk_add_f32 v[28:29], v[28:29], 1.0 op_sel_hi:[1,0]
	v_pk_fma_f32 v[30:31], v[30:31], v[26:27], v[74:75]
	v_pk_fma_f32 v[26:27], v[28:29], v[24:25], v[72:73]
	v_lshl_add_u64 v[28:29], v[48:49], 0, v[44:45]
	v_add_co_u32_e32 v28, vcc, s30, v28
	v_cvt_pk_bf16_f32 v24, v76, v77
	v_cvt_pk_bf16_f32 v25, v60, v61
	v_cvt_pk_bf16_f32 v26, v26, v27
	v_cvt_pk_bf16_f32 v27, v30, v31
	v_addc_co_u32_e32 v29, vcc, 0, v29, vcc
	flat_store_dwordx4 v[28:29], v[24:27]
	s_nop 1
	v_mov_b64_e32 v[24:25], v[120:121]
	v_mov_b64_e32 v[26:27], v[122:123]
	s_nop 0
	s_nop 1
	v_mov_b64_e32 v[68:69], v[124:125]
	v_mov_b64_e32 v[70:71], v[126:127]
	s_nop 1
	v_mov_b64_e32 v[72:73], v[128:129]
	v_mov_b64_e32 v[74:75], v[130:131]
	s_nop 1
	v_mov_b64_e32 v[76:77], v[132:133]
	v_mov_b64_e32 v[78:79], v[134:135]
	s_mov_b32 s30, 0x8800
	v_cmp_gt_i32_e32 vcc, s30, v33
	s_waitcnt vmcnt(0)
	v_pk_mul_f32 v[20:21], v[24:25], v[20:21]
	v_pk_mul_f32 v[16:17], v[68:69], v[16:17]
	v_pk_mul_f32 v[18:19], v[70:71], v[18:19]
	s_waitcnt lgkmcnt(0)
	v_pk_add_f32 v[30:31], v[74:75], 1.0 op_sel_hi:[1,0]
	v_pk_add_f32 v[60:61], v[72:73], 1.0 op_sel_hi:[1,0]
	v_pk_fma_f32 v[30:31], v[30:31], v[18:19], v[78:79]
	v_pk_fma_f32 v[60:61], v[60:61], v[16:17], v[76:77]
	s_nop 1
	v_mov_b64_e32 v[16:17], v[136:137]
	v_mov_b64_e32 v[18:19], v[138:139]
	s_nop 0
	s_nop 1
	v_mov_b64_e32 v[54:55], v[140:141]
	v_mov_b64_e32 v[56:57], v[142:143]
	v_pk_mul_f32 v[22:23], v[26:27], v[22:23]
	s_waitcnt vmcnt(0) lgkmcnt(0)
	v_pk_add_f32 v[18:19], v[18:19], 1.0 op_sel_hi:[1,0]
	v_pk_add_f32 v[16:17], v[16:17], 1.0 op_sel_hi:[1,0]
	v_pk_fma_f32 v[22:23], v[22:23], v[18:19], v[56:57]
	v_pk_fma_f32 v[18:19], v[20:21], v[16:17], v[54:55]
	v_cvt_pk_bf16_f32 v16, v60, v61
	v_cvt_pk_bf16_f32 v17, v30, v31
	v_cvt_pk_bf16_f32 v18, v18, v19
	v_cvt_pk_bf16_f32 v19, v22, v23
	flat_store_dwordx4 v[28:29], v[16:19] offset:1024
	s_and_saveexec_b64 s[44:45], vcc
	s_cbranch_execz .LBB0_974
	v_min_i32_e32 v16, 0x8000, v33
	v_ashrrev_i32_e32 v16, 12, v16
	v_mul_i32_i24_e32 v16, 9, v16
	v_add_f32_e32 v20, v53, v58
	v_ashrrev_i32_e32 v17, 31, v16
	v_lshlrev_b64 v[18:19], 12, v[16:17]
	v_fmamk_f32 v16, v20, 0x3a800000, v191
	s_mov_b32 s30, 0x800000
	v_cmp_gt_f32_e32 vcc, s30, v16
	v_mul_f32_e32 v17, 0x4b800000, v16
	v_lshl_add_u64 v[30:31], v[42:43], 0, v[18:19]
	v_cndmask_b32_e32 v16, v16, v17, vcc
	v_rsq_f32_e32 v16, v16
	s_movk_i32 s30, 0x4000
	s_mov_b64 s[42:43], 0x4000
	v_lshl_add_u64 v[20:21], v[30:31], 0, s[42:43]
	v_mul_f32_e32 v17, 0x45800000, v16
	v_cndmask_b32_e32 v16, v16, v17, vcc
	v_add_co_u32_e32 v52, vcc, s30, v30
	s_mov_b64 s[42:43], 0x3000
	s_nop 0
	v_addc_co_u32_e32 v53, vcc, 0, v31, vcc
	s_movk_i32 s30, 0x3000
	v_lshl_add_u64 v[18:19], v[30:31], 0, s[42:43]
	v_add_co_u32_e32 v30, vcc, s30, v30
	global_load_dwordx4 v[22:25], v[38:39], off offset:16
	global_load_dwordx4 v[26:29], v[38:39], off
	v_addc_co_u32_e32 v31, vcc, 0, v31, vcc
	flat_load_dwordx4 v[52:55], v[52:53]
	v_pk_mul_f32 v[14:15], v[14:15], v[16:17] op_sel_hi:[1,0]
	flat_load_dwordx4 v[56:59], v[30:31]
	global_load_dwordx4 v[144:147], v[20:21], off offset:16
	global_load_dwordx4 v[148:151], v[18:19], off offset:16
	global_load_dwordx4 v[152:155], v[40:41], off offset:16
	global_load_dwordx4 v[156:159], v[40:41], off
	global_load_dwordx4 v[160:163], v[20:21], off offset:2048
	global_load_dwordx4 v[164:167], v[18:19], off offset:2048
	global_load_dwordx4 v[168:171], v[20:21], off offset:2064
	global_load_dwordx4 v[172:175], v[18:19], off offset:2064
	v_pk_mul_f32 v[12:13], v[12:13], v[16:17] op_sel_hi:[1,0]
	v_pk_mul_f32 v[10:11], v[10:11], v[16:17] op_sel_hi:[1,0]
	v_pk_mul_f32 v[8:9], v[8:9], v[16:17] op_sel_hi:[1,0]
	s_mov_b32 s30, 0xc944000
	v_pk_mul_f32 v[2:3], v[2:3], v[16:17] op_sel_hi:[1,0]
	v_pk_mul_f32 v[0:1], v[0:1], v[16:17] op_sel_hi:[1,0]
	v_pk_mul_f32 v[6:7], v[6:7], v[16:17] op_sel_hi:[1,0]
	v_pk_mul_f32 v[4:5], v[4:5], v[16:17] op_sel_hi:[1,0]
	s_waitcnt vmcnt(0)
	v_pk_mul_f32 v[8:9], v[8:9], v[22:23]
	v_pk_mul_f32 v[12:13], v[12:13], v[26:27]
	v_pk_mul_f32 v[14:15], v[14:15], v[28:29]
	v_pk_mul_f32 v[10:11], v[10:11], v[24:25]
	s_waitcnt lgkmcnt(0)
	v_pk_add_f32 v[26:27], v[54:55], 1.0 op_sel_hi:[1,0]
	v_pk_add_f32 v[28:29], v[52:53], 1.0 op_sel_hi:[1,0]
	v_pk_fma_f32 v[30:31], v[14:15], v[26:27], v[58:59]
	v_pk_fma_f32 v[52:53], v[12:13], v[28:29], v[56:57]
	s_nop 1
	v_mov_b64_e32 v[12:13], v[144:145]
	v_mov_b64_e32 v[14:15], v[146:147]
	s_nop 1
	v_mov_b64_e32 v[26:27], v[148:149]
	v_mov_b64_e32 v[28:29], v[150:151]
	s_waitcnt vmcnt(0) lgkmcnt(0)
	v_pk_add_f32 v[14:15], v[14:15], 1.0 op_sel_hi:[1,0]
	v_pk_add_f32 v[12:13], v[12:13], 1.0 op_sel_hi:[1,0]
	v_pk_fma_f32 v[14:15], v[10:11], v[14:15], v[28:29]
	v_pk_fma_f32 v[10:11], v[8:9], v[12:13], v[26:27]
	v_lshl_add_u64 v[12:13], v[46:47], 0, v[44:45]
	v_cvt_pk_bf16_f32 v9, v30, v31
	v_add_co_u32_e32 v30, vcc, s30, v12
	v_cvt_pk_bf16_f32 v8, v52, v53
	v_cvt_pk_bf16_f32 v10, v10, v11
	v_cvt_pk_bf16_f32 v11, v14, v15
	v_addc_co_u32_e32 v31, vcc, 0, v13, vcc
	flat_store_dwordx4 v[30:31], v[8:11]
	s_nop 1
	v_mov_b64_e32 v[8:9], v[152:153]
	v_mov_b64_e32 v[10:11], v[154:155]
	s_nop 0
	s_nop 1
	v_mov_b64_e32 v[12:13], v[156:157]
	v_mov_b64_e32 v[14:15], v[158:159]
	s_nop 1
	v_mov_b64_e32 v[22:23], v[160:161]
	v_mov_b64_e32 v[24:25], v[162:163]
	s_nop 1
	v_mov_b64_e32 v[26:27], v[164:165]
	v_mov_b64_e32 v[28:29], v[166:167]
	s_waitcnt vmcnt(0)
	v_pk_mul_f32 v[4:5], v[4:5], v[8:9]
	v_pk_mul_f32 v[0:1], v[0:1], v[12:13]
	v_pk_mul_f32 v[2:3], v[2:3], v[14:15]
	s_waitcnt lgkmcnt(0)
	v_pk_add_f32 v[12:13], v[24:25], 1.0 op_sel_hi:[1,0]
	v_pk_add_f32 v[14:15], v[22:23], 1.0 op_sel_hi:[1,0]
	v_pk_fma_f32 v[22:23], v[2:3], v[12:13], v[28:29]
	v_pk_fma_f32 v[24:25], v[0:1], v[14:15], v[26:27]
	s_nop 1
	v_mov_b64_e32 v[0:1], v[168:169]
	v_mov_b64_e32 v[2:3], v[170:171]
	s_nop 1
	v_mov_b64_e32 v[12:13], v[172:173]
	v_mov_b64_e32 v[14:15], v[174:175]
	v_pk_mul_f32 v[6:7], v[6:7], v[10:11]
	s_waitcnt vmcnt(0) lgkmcnt(0)
	v_pk_add_f32 v[2:3], v[2:3], 1.0 op_sel_hi:[1,0]
	v_pk_add_f32 v[0:1], v[0:1], 1.0 op_sel_hi:[1,0]
	v_pk_fma_f32 v[6:7], v[6:7], v[2:3], v[14:15]
	v_pk_fma_f32 v[2:3], v[4:5], v[0:1], v[12:13]
	v_cvt_pk_bf16_f32 v0, v24, v25
	v_cvt_pk_bf16_f32 v1, v22, v23
	v_cvt_pk_bf16_f32 v2, v2, v3
	v_cvt_pk_bf16_f32 v3, v6, v7
	flat_store_dwordx4 v[30:31], v[0:3] offset:1024
	s_branch .LBB0_974

.LBB0_2542:
	s_or_b64 exec, exec, s[50:51]
	s_waitcnt vmcnt(0) lgkmcnt(0)
	v_mul_f32_e32 v52, v29, v29
	v_mul_f32_e32 v53, v25, v25
	v_fmac_f32_e32 v52, v28, v28
	v_fmac_f32_e32 v53, v24, v24
	v_fmac_f32_e32 v52, v30, v30
	v_fmac_f32_e32 v53, v26, v26
	v_fmac_f32_e32 v52, v31, v31
	v_fmac_f32_e32 v53, v27, v27
	v_add_f32_e32 v52, v53, v52
	v_mul_f32_e32 v53, v17, v17
	v_fmac_f32_e32 v53, v16, v16
	v_fmac_f32_e32 v53, v18, v18
	v_fmac_f32_e32 v53, v19, v19
	v_add_f32_e32 v52, v53, v52
	v_mul_f32_e32 v53, v21, v21
	v_fmac_f32_e32 v53, v20, v20
	v_fmac_f32_e32 v53, v22, v22
	v_fmac_f32_e32 v53, v23, v23
	v_add_f32_e32 v52, v53, v52
	v_mul_f32_e32 v53, v13, v13
	v_mul_f32_e32 v54, v9, v9
	v_fmac_f32_e32 v53, v12, v12
	v_fmac_f32_e32 v54, v8, v8
	v_fmac_f32_e32 v53, v14, v14
	v_fmac_f32_e32 v54, v10, v10
	v_fmac_f32_e32 v53, v15, v15
	v_fmac_f32_e32 v54, v11, v11
	v_add_f32_e32 v53, v54, v53
	v_mul_f32_e32 v54, v1, v1
	v_fmac_f32_e32 v54, v0, v0
	v_fmac_f32_e32 v54, v2, v2
	v_fmac_f32_e32 v54, v3, v3
	v_add_f32_e32 v53, v54, v53
	v_mul_f32_e32 v54, v5, v5
	v_fmac_f32_e32 v54, v4, v4
	v_fmac_f32_e32 v54, v6, v6
	v_fmac_f32_e32 v54, v7, v7
	v_add_f32_e32 v53, v54, v53
	ds_bpermute_b32 v54, v35, v52
	s_mov_b32 s30, 0x800000
	s_mov_b64 s[40:41], 0x7000
	global_load_dwordx4 v[68:71], v[38:39], off offset:16
	global_load_dwordx4 v[72:75], v[38:39], off
	s_waitcnt lgkmcnt(0)
	v_add_f32_e32 v52, v52, v54
	ds_bpermute_b32 v54, v35, v53
	s_waitcnt lgkmcnt(0)
	v_add_f32_e32 v53, v53, v54
	ds_bpermute_b32 v54, v62, v52
	s_waitcnt lgkmcnt(0)
	v_add_f32_e32 v52, v52, v54
	ds_bpermute_b32 v54, v62, v53
	s_waitcnt lgkmcnt(0)
	v_add_f32_e32 v53, v53, v54
	ds_bpermute_b32 v54, v63, v52
	s_waitcnt lgkmcnt(0)
	v_add_f32_e32 v52, v52, v54
	ds_bpermute_b32 v54, v63, v53
	s_waitcnt lgkmcnt(0)
	v_add_f32_e32 v53, v53, v54
	ds_bpermute_b32 v54, v64, v52
	s_waitcnt lgkmcnt(0)
	v_add_f32_e32 v52, v52, v54
	ds_bpermute_b32 v54, v64, v53
	s_waitcnt lgkmcnt(0)
	v_add_f32_e32 v53, v53, v54
	ds_bpermute_b32 v54, v65, v52
	s_waitcnt lgkmcnt(0)
	v_add_f32_e32 v52, v52, v54
	ds_bpermute_b32 v54, v65, v53
	s_waitcnt lgkmcnt(0)
	v_add_f32_e32 v53, v53, v54
	ds_bpermute_b32 v54, v66, v52
	ds_bpermute_b32 v58, v66, v53
	s_waitcnt lgkmcnt(1)
	v_add_f32_e32 v52, v52, v54
	v_fmamk_f32 v52, v52, 0x3a800000, v191
	v_cmp_gt_f32_e32 vcc, s30, v52
	v_mul_f32_e32 v56, 0x4b800000, v52
	v_min_i32_e32 v54, 0x8000, v32
	v_cndmask_b32_e32 v52, v52, v56, vcc
	v_ashrrev_i32_e32 v54, 12, v54
	v_rsq_f32_e32 v52, v52
	v_mul_i32_i24_e32 v54, 9, v54
	v_ashrrev_i32_e32 v55, 31, v54
	v_lshlrev_b64 v[54:55], 12, v[54:55]
	v_mul_f32_e32 v56, 0x45800000, v52
	v_lshl_add_u64 v[60:61], v[42:43], 0, v[54:55]
	s_movk_i32 s30, 0x7000
	v_cndmask_b32_e32 v52, v52, v56, vcc
	v_add_co_u32_e32 v76, vcc, s30, v60
	v_lshl_add_u64 v[56:57], v[60:61], 0, s[40:41]
	s_mov_b64 s[40:41], 0x6000
	v_addc_co_u32_e32 v77, vcc, 0, v61, vcc
	s_movk_i32 s30, 0x6000
	v_lshl_add_u64 v[54:55], v[60:61], 0, s[40:41]
	v_add_co_u32_e32 v60, vcc, s30, v60
	flat_load_dwordx4 v[76:79], v[76:77]
	s_nop 0
	v_addc_co_u32_e32 v61, vcc, 0, v61, vcc
	flat_load_dwordx4 v[80:83], v[60:61]
	global_load_dwordx4 v[112:115], v[56:57], off offset:16
	global_load_dwordx4 v[116:119], v[54:55], off offset:16
	global_load_dwordx4 v[120:123], v[40:41], off offset:16
	global_load_dwordx4 v[124:127], v[40:41], off
	global_load_dwordx4 v[128:131], v[56:57], off offset:2048
	global_load_dwordx4 v[132:135], v[54:55], off offset:2048
	global_load_dwordx4 v[136:139], v[56:57], off offset:2064
	global_load_dwordx4 v[140:143], v[54:55], off offset:2064
	v_pk_mul_f32 v[30:31], v[30:31], v[52:53] op_sel_hi:[1,0]
	v_pk_mul_f32 v[28:29], v[28:29], v[52:53] op_sel_hi:[1,0]
	s_waitcnt vmcnt(0)
	v_pk_mul_f32 v[30:31], v[74:75], v[30:31]
	v_pk_mul_f32 v[28:29], v[72:73], v[28:29]
	v_pk_mul_f32 v[26:27], v[26:27], v[52:53] op_sel_hi:[1,0]
	v_pk_mul_f32 v[24:25], v[24:25], v[52:53] op_sel_hi:[1,0]
	v_pk_mul_f32 v[26:27], v[70:71], v[26:27]
	v_pk_mul_f32 v[24:25], v[68:69], v[24:25]
	s_mov_b32 s30, 0xc944000
	v_pk_mul_f32 v[18:19], v[18:19], v[52:53] op_sel_hi:[1,0]
	v_pk_mul_f32 v[16:17], v[16:17], v[52:53] op_sel_hi:[1,0]
	v_pk_mul_f32 v[22:23], v[22:23], v[52:53] op_sel_hi:[1,0]
	v_pk_mul_f32 v[20:21], v[20:21], v[52:53] op_sel_hi:[1,0]
	s_waitcnt lgkmcnt(0)
	v_pk_add_f32 v[60:61], v[78:79], 1.0 op_sel_hi:[1,0]
	v_pk_add_f32 v[72:73], v[76:77], 1.0 op_sel_hi:[1,0]
	v_pk_fma_f32 v[60:61], v[60:61], v[30:31], v[82:83]
	v_pk_fma_f32 v[76:77], v[72:73], v[28:29], v[80:81]
	s_nop 1
	v_mov_b64_e32 v[28:29], v[112:113]
	v_mov_b64_e32 v[30:31], v[114:115]
	s_nop 1
	v_mov_b64_e32 v[72:73], v[116:117]
	v_mov_b64_e32 v[74:75], v[118:119]
	s_waitcnt vmcnt(0) lgkmcnt(0)
	v_pk_add_f32 v[30:31], v[30:31], 1.0 op_sel_hi:[1,0]
	v_pk_add_f32 v[28:29], v[28:29], 1.0 op_sel_hi:[1,0]
	v_pk_fma_f32 v[30:31], v[30:31], v[26:27], v[74:75]
	v_pk_fma_f32 v[26:27], v[28:29], v[24:25], v[72:73]
	v_lshl_add_u64 v[28:29], v[48:49], 0, v[44:45]
	v_add_co_u32_e32 v28, vcc, s30, v28
	v_cvt_pk_bf16_f32 v24, v76, v77
	v_cvt_pk_bf16_f32 v25, v60, v61
	v_cvt_pk_bf16_f32 v26, v26, v27
	v_cvt_pk_bf16_f32 v27, v30, v31
	v_addc_co_u32_e32 v29, vcc, 0, v29, vcc
	flat_store_dwordx4 v[28:29], v[24:27]
	s_nop 1
	v_mov_b64_e32 v[24:25], v[120:121]
	v_mov_b64_e32 v[26:27], v[122:123]
	s_nop 0
	s_nop 1
	v_mov_b64_e32 v[68:69], v[124:125]
	v_mov_b64_e32 v[70:71], v[126:127]
	s_nop 1
	v_mov_b64_e32 v[72:73], v[128:129]
	v_mov_b64_e32 v[74:75], v[130:131]
	s_nop 1
	v_mov_b64_e32 v[76:77], v[132:133]
	v_mov_b64_e32 v[78:79], v[134:135]
	s_mov_b32 s30, 0x8800
	v_cmp_gt_i32_e32 vcc, s30, v33
	s_waitcnt vmcnt(0)
	v_pk_mul_f32 v[20:21], v[24:25], v[20:21]
	v_pk_mul_f32 v[16:17], v[68:69], v[16:17]
	v_pk_mul_f32 v[18:19], v[70:71], v[18:19]
	s_waitcnt lgkmcnt(0)
	v_pk_add_f32 v[30:31], v[74:75], 1.0 op_sel_hi:[1,0]
	v_pk_add_f32 v[60:61], v[72:73], 1.0 op_sel_hi:[1,0]
	v_pk_fma_f32 v[30:31], v[30:31], v[18:19], v[78:79]
	v_pk_fma_f32 v[60:61], v[60:61], v[16:17], v[76:77]
	s_nop 1
	v_mov_b64_e32 v[16:17], v[136:137]
	v_mov_b64_e32 v[18:19], v[138:139]
	s_nop 0
	s_nop 1
	v_mov_b64_e32 v[54:55], v[140:141]
	v_mov_b64_e32 v[56:57], v[142:143]
	v_pk_mul_f32 v[22:23], v[26:27], v[22:23]
	s_waitcnt vmcnt(0) lgkmcnt(0)
	v_pk_add_f32 v[18:19], v[18:19], 1.0 op_sel_hi:[1,0]
	v_pk_add_f32 v[16:17], v[16:17], 1.0 op_sel_hi:[1,0]
	v_pk_fma_f32 v[22:23], v[22:23], v[18:19], v[56:57]
	v_pk_fma_f32 v[18:19], v[20:21], v[16:17], v[54:55]
	v_cvt_pk_bf16_f32 v16, v60, v61
	v_cvt_pk_bf16_f32 v17, v30, v31
	v_cvt_pk_bf16_f32 v18, v18, v19
	v_cvt_pk_bf16_f32 v19, v22, v23
	flat_store_dwordx4 v[28:29], v[16:19] offset:1024
	s_and_saveexec_b64 s[50:51], vcc
	s_cbranch_execz .LBB0_2537
	v_min_i32_e32 v16, 0x8000, v33
	v_ashrrev_i32_e32 v16, 12, v16
	v_mul_i32_i24_e32 v16, 9, v16
	v_add_f32_e32 v20, v53, v58
	v_ashrrev_i32_e32 v17, 31, v16
	v_lshlrev_b64 v[18:19], 12, v[16:17]
	v_fmamk_f32 v16, v20, 0x3a800000, v191
	s_mov_b32 s30, 0x800000
	v_cmp_gt_f32_e32 vcc, s30, v16
	v_mul_f32_e32 v17, 0x4b800000, v16
	v_lshl_add_u64 v[30:31], v[42:43], 0, v[18:19]
	v_cndmask_b32_e32 v16, v16, v17, vcc
	v_rsq_f32_e32 v16, v16
	s_movk_i32 s30, 0x7000
	s_mov_b64 s[40:41], 0x7000
	v_lshl_add_u64 v[20:21], v[30:31], 0, s[40:41]
	v_mul_f32_e32 v17, 0x45800000, v16
	v_cndmask_b32_e32 v16, v16, v17, vcc
	v_add_co_u32_e32 v52, vcc, s30, v30
	s_mov_b64 s[40:41], 0x6000
	s_nop 0
	v_addc_co_u32_e32 v53, vcc, 0, v31, vcc
	s_movk_i32 s30, 0x6000
	v_lshl_add_u64 v[18:19], v[30:31], 0, s[40:41]
	v_add_co_u32_e32 v30, vcc, s30, v30
	global_load_dwordx4 v[22:25], v[38:39], off offset:16
	global_load_dwordx4 v[26:29], v[38:39], off
	v_addc_co_u32_e32 v31, vcc, 0, v31, vcc
	flat_load_dwordx4 v[52:55], v[52:53]
	v_pk_mul_f32 v[14:15], v[14:15], v[16:17] op_sel_hi:[1,0]
	flat_load_dwordx4 v[56:59], v[30:31]
	global_load_dwordx4 v[144:147], v[20:21], off offset:16
	global_load_dwordx4 v[148:151], v[18:19], off offset:16
	global_load_dwordx4 v[152:155], v[40:41], off offset:16
	global_load_dwordx4 v[156:159], v[40:41], off
	global_load_dwordx4 v[160:163], v[20:21], off offset:2048
	global_load_dwordx4 v[164:167], v[18:19], off offset:2048
	global_load_dwordx4 v[168:171], v[20:21], off offset:2064
	global_load_dwordx4 v[172:175], v[18:19], off offset:2064
	v_pk_mul_f32 v[12:13], v[12:13], v[16:17] op_sel_hi:[1,0]
	v_pk_mul_f32 v[10:11], v[10:11], v[16:17] op_sel_hi:[1,0]
	v_pk_mul_f32 v[8:9], v[8:9], v[16:17] op_sel_hi:[1,0]
	s_mov_b32 s30, 0xc944000
	v_pk_mul_f32 v[2:3], v[2:3], v[16:17] op_sel_hi:[1,0]
	v_pk_mul_f32 v[0:1], v[0:1], v[16:17] op_sel_hi:[1,0]
	v_pk_mul_f32 v[6:7], v[6:7], v[16:17] op_sel_hi:[1,0]
	v_pk_mul_f32 v[4:5], v[4:5], v[16:17] op_sel_hi:[1,0]
	s_waitcnt vmcnt(0)
	v_pk_mul_f32 v[8:9], v[8:9], v[22:23]
	v_pk_mul_f32 v[12:13], v[12:13], v[26:27]
	v_pk_mul_f32 v[14:15], v[14:15], v[28:29]
	v_pk_mul_f32 v[10:11], v[10:11], v[24:25]
	s_waitcnt lgkmcnt(0)
	v_pk_add_f32 v[26:27], v[54:55], 1.0 op_sel_hi:[1,0]
	v_pk_add_f32 v[28:29], v[52:53], 1.0 op_sel_hi:[1,0]
	v_pk_fma_f32 v[30:31], v[14:15], v[26:27], v[58:59]
	v_pk_fma_f32 v[52:53], v[12:13], v[28:29], v[56:57]
	s_nop 1
	v_mov_b64_e32 v[12:13], v[144:145]
	v_mov_b64_e32 v[14:15], v[146:147]
	s_nop 1
	v_mov_b64_e32 v[26:27], v[148:149]
	v_mov_b64_e32 v[28:29], v[150:151]
	s_waitcnt vmcnt(0) lgkmcnt(0)
	v_pk_add_f32 v[14:15], v[14:15], 1.0 op_sel_hi:[1,0]
	v_pk_add_f32 v[12:13], v[12:13], 1.0 op_sel_hi:[1,0]
	v_pk_fma_f32 v[14:15], v[10:11], v[14:15], v[28:29]
	v_pk_fma_f32 v[10:11], v[8:9], v[12:13], v[26:27]
	v_lshl_add_u64 v[12:13], v[46:47], 0, v[44:45]
	v_cvt_pk_bf16_f32 v9, v30, v31
	v_add_co_u32_e32 v30, vcc, s30, v12
	v_cvt_pk_bf16_f32 v8, v52, v53
	v_cvt_pk_bf16_f32 v10, v10, v11
	v_cvt_pk_bf16_f32 v11, v14, v15
	v_addc_co_u32_e32 v31, vcc, 0, v13, vcc
	flat_store_dwordx4 v[30:31], v[8:11]
	s_nop 1
	v_mov_b64_e32 v[8:9], v[152:153]
	v_mov_b64_e32 v[10:11], v[154:155]
	s_nop 0
	s_nop 1
	v_mov_b64_e32 v[12:13], v[156:157]
	v_mov_b64_e32 v[14:15], v[158:159]
	s_nop 1
	v_mov_b64_e32 v[22:23], v[160:161]
	v_mov_b64_e32 v[24:25], v[162:163]
	s_nop 1
	v_mov_b64_e32 v[26:27], v[164:165]
	v_mov_b64_e32 v[28:29], v[166:167]
	s_waitcnt vmcnt(0)
	v_pk_mul_f32 v[4:5], v[4:5], v[8:9]
	v_pk_mul_f32 v[0:1], v[0:1], v[12:13]
	v_pk_mul_f32 v[2:3], v[2:3], v[14:15]
	s_waitcnt lgkmcnt(0)
	v_pk_add_f32 v[12:13], v[24:25], 1.0 op_sel_hi:[1,0]
	v_pk_add_f32 v[14:15], v[22:23], 1.0 op_sel_hi:[1,0]
	v_pk_fma_f32 v[22:23], v[2:3], v[12:13], v[28:29]
	v_pk_fma_f32 v[24:25], v[0:1], v[14:15], v[26:27]
	s_nop 1
	v_mov_b64_e32 v[0:1], v[168:169]
	v_mov_b64_e32 v[2:3], v[170:171]
	s_nop 1
	v_mov_b64_e32 v[12:13], v[172:173]
	v_mov_b64_e32 v[14:15], v[174:175]
	v_pk_mul_f32 v[6:7], v[6:7], v[10:11]
	s_waitcnt vmcnt(0) lgkmcnt(0)
	v_pk_add_f32 v[2:3], v[2:3], 1.0 op_sel_hi:[1,0]
	v_pk_add_f32 v[0:1], v[0:1], 1.0 op_sel_hi:[1,0]
	v_pk_fma_f32 v[6:7], v[6:7], v[2:3], v[14:15]
	v_pk_fma_f32 v[2:3], v[4:5], v[0:1], v[12:13]
	v_cvt_pk_bf16_f32 v0, v24, v25
	v_cvt_pk_bf16_f32 v1, v22, v23
	v_cvt_pk_bf16_f32 v2, v2, v3
	v_cvt_pk_bf16_f32 v3, v6, v7
	flat_store_dwordx4 v[30:31], v[0:3] offset:1024
	s_branch .LBB0_2537
